# hoisted residual epilogues: drop the vmcnt waits that only guarded the (now earlier) second-half loads so stores are not throttled
# speedup vs baseline: 1.0156x; 1.0035x over previous
; __device__ __forceinline__ u32x4 pack8(f32x4 a, f32x4 b) { u32x4 w; w.x = cvtpk(a[0], a[1]); w.y = cvtpk(a[2], a[3]); w.z = cvtpk(b[0], b[1]); w.w = cvtpk(b[2], b[3]); return w; }
;     __device__ __forceinline__ void operator()(AccRef acc, const Unit& u, int wr, int wc, int fr, int fq) const {
;     ...
;             for (int m = 0; m < 4; ++m) {
;                 const int row = u.pm * 256 + ai * 128 + wr * 64 + m * 16 + fr; float part = 0.f;
;                 const float sc = RS ? scale * rst[u.ui * 256 + ai * 128 + wr * 64 + m * 16 + fr] : scale;
; #pragma unroll
;                 for (int bj = 0; bj < 2; ++bj) {
;                     const size_t idx = (size_t)row * D + u.pn * 256 + bj * 128 + wc * 32 + 8 * fq;
;                     const u32x4 o4 = ow[m][bj];
;                     f32x4 v0, v1;
;                     v0[0] = __uint_as_float(o4.x << 16); v0[1] = __uint_as_float(o4.x & 0xffff0000u); v0[2] = __uint_as_float(o4.y << 16); v0[3] = __uint_as_float(o4.y & 0xffff0000u);
;                     v1[0] = __uint_as_float(o4.z << 16); v1[1] = __uint_as_float(o4.z & 0xffff0000u); v1[2] = __uint_as_float(o4.w << 16); v1[3] = __uint_as_float(o4.w & 0xffff0000u);
;                     v0 = v0 + acc[ai][bj][m][0] * sc; v1 = v1 + acc[ai][bj][m][1] * sc;
;                     *(u32x4*)(hb + idx) = pack8(v0, v1);
;                     part += (v0[0] * v0[0] + v0[1] * v0[1]) + (v0[2] * v0[2] + v0[3] * v0[3]) + (v1[0] * v1[0] + v1[1] * v1[1]) + (v1[2] * v1[2] + v1[3] * v1[3]);
;                 }
;                 part = fq_sum(part);
;                 if (fq == 0) ssn[(size_t)row * 16 + u.pn * 4 + wc] = part;
.LBB0_618:
	s_or_b64 exec, exec, s[62:63]
	v_add_u32_e32 v102, 0x80, v154
	v_ashrrev_i32_e32 v103, 31, v102
	v_add_u32_e32 v98, 0x90, v154
	v_lshlrev_b64 v[112:113], 11, v[102:103]
	v_ashrrev_i32_e32 v99, 31, v98
	v_add_u32_e32 v94, 0xa0, v154
	v_lshl_add_u64 v[66:67], v[156:157], 0, v[112:113]
	v_lshlrev_b64 v[100:101], 11, v[98:99]
	v_ashrrev_i32_e32 v95, 31, v94
	v_add_u32_e32 v90, 0xb0, v154
	v_lshl_add_u64 v[66:67], v[156:157], 0, v[100:101]
	v_lshlrev_b64 v[96:97], 11, v[94:95]
	v_ashrrev_i32_e32 v91, 31, v90
	v_lshl_add_u64 v[66:67], v[156:157], 0, v[96:97]
	v_lshlrev_b64 v[92:93], 11, v[90:91]
	v_lshl_add_u64 v[66:67], v[156:157], 0, v[92:93]
	s_nop 0
	v_lshl_add_u64 v[112:113], s[10:11], 0, v[112:113]
	v_lshlrev_b32_e32 v114, 16, v196
	v_and_b32_e32 v115, 0xffff0000, v196
	v_lshlrev_b32_e32 v104, 16, v197
	v_and_b32_e32 v105, 0xffff0000, v197
	v_lshlrev_b32_e32 v116, 16, v198
	v_and_b32_e32 v117, 0xffff0000, v198
	v_lshlrev_b32_e32 v106, 16, v199
	v_and_b32_e32 v107, 0xffff0000, v199
	v_lshl_add_u64 v[112:113], s[60:61], 1, v[112:113]
	v_pk_fma_f32 v[64:65], v[64:65], 0.5, v[104:105] op_sel_hi:[1,0,1]
	v_pk_fma_f32 v[62:63], v[62:63], 0.5, v[114:115] op_sel_hi:[1,0,1]
	v_pk_fma_f32 v[104:105], v[60:61], 0.5, v[106:107] op_sel_hi:[1,0,1]
	v_pk_fma_f32 v[106:107], v[58:59], 0.5, v[116:117] op_sel_hi:[1,0,1]
	v_lshl_add_u64 v[112:113], v[112:113], 0, s[18:19]
	v_cvt_pk_bf16_f32 v58, v62, v63
	v_cvt_pk_bf16_f32 v59, v64, v65
	v_cvt_pk_bf16_f32 v60, v106, v107
	v_cvt_pk_bf16_f32 v61, v104, v105
	v_lshl_add_u64 v[112:113], v[112:113], 0, v[0:1]
	global_store_dwordx4 v[112:113], v[58:61], off
	s_nop 1
	v_mul_f32_e32 v58, v63, v63
	v_mul_f32_e32 v59, v65, v65
	v_fmac_f32_e32 v58, v62, v62
	v_fmac_f32_e32 v59, v64, v64
	v_add_f32_e32 v58, v58, v59
	v_mul_f32_e32 v59, v107, v107
	v_fmac_f32_e32 v59, v106, v106
	v_add_f32_e32 v58, v59, v58
	v_mul_f32_e32 v59, v105, v105
	v_fmac_f32_e32 v59, v104, v104
	v_add_f32_e32 v104, v59, v58
	v_lshlrev_b32_e32 v58, 16, v200
	v_and_b32_e32 v59, 0xffff0000, v200
	v_lshlrev_b32_e32 v60, 16, v201
	v_and_b32_e32 v61, 0xffff0000, v201
	v_lshlrev_b32_e32 v62, 16, v202
	v_and_b32_e32 v63, 0xffff0000, v202
	v_lshlrev_b32_e32 v64, 16, v203
	v_and_b32_e32 v65, 0xffff0000, v203
	v_pk_fma_f32 v[56:57], v[56:57], 0.5, v[60:61] op_sel_hi:[1,0,1]
	v_pk_fma_f32 v[54:55], v[54:55], 0.5, v[58:59] op_sel_hi:[1,0,1]
	v_pk_fma_f32 v[58:59], v[52:53], 0.5, v[64:65] op_sel_hi:[1,0,1]
	v_pk_fma_f32 v[60:61], v[50:51], 0.5, v[62:63] op_sel_hi:[1,0,1]
	v_cvt_pk_bf16_f32 v50, v54, v55
	v_cvt_pk_bf16_f32 v51, v56, v57
	v_cvt_pk_bf16_f32 v52, v60, v61
	v_cvt_pk_bf16_f32 v53, v58, v59
	global_store_dwordx4 v[112:113], v[50:53], off offset:256
	s_nop 1
	v_mul_f32_e32 v50, v55, v55
	v_mul_f32_e32 v51, v57, v57
	v_fmac_f32_e32 v50, v54, v54
	v_fmac_f32_e32 v51, v56, v56
	v_add_f32_e32 v50, v50, v51
	v_mul_f32_e32 v51, v61, v61
	v_fmac_f32_e32 v51, v60, v60
	v_add_f32_e32 v50, v51, v50
	v_mul_f32_e32 v51, v59, v59
	v_fmac_f32_e32 v51, v58, v58
	v_add_f32_e32 v50, v51, v50
	v_add_f32_e32 v50, v104, v50
	v_mov_b32_e32 v51, v50
	s_nop 1
	v_permlane32_swap_b32_e32 v50, v51
	v_add_f32_e32 v50, v50, v51
	v_mov_b32_e32 v51, v50
	s_nop 1
	v_permlane16_swap_b32_e32 v50, v51
	s_and_saveexec_b64 s[62:63], vcc
	s_cbranch_execz .LBB0_620
	v_lshlrev_b64 v[52:53], 6, v[102:103]
	v_lshl_add_u64 v[52:53], s[12:13], 0, v[52:53]
	v_lshl_add_u64 v[52:53], s[58:59], 2, v[52:53]
	s_lshl_b32 s76, s45, 2
	s_mov_b32 s77, s19
	v_lshl_add_u64 v[52:53], v[52:53], 0, s[76:77]
	v_add_f32_e32 v50, v50, v51
	global_store_dword v[52:53], v50, off
.LBB0_620:
	s_or_b64 exec, exec, s[62:63]
	v_lshlrev_b32_e32 v52, 16, v207
	v_and_b32_e32 v53, 0xffff0000, v207
	v_lshlrev_b32_e32 v54, 16, v208
	v_and_b32_e32 v55, 0xffff0000, v208
	v_pk_fma_f32 v[48:49], v[48:49], 0.5, v[52:53] op_sel_hi:[1,0,1]
	v_pk_fma_f32 v[52:53], v[42:43], 0.5, v[54:55] op_sel_hi:[1,0,1]
	v_lshl_add_u64 v[54:55], s[10:11], 0, v[100:101]
	v_lshlrev_b32_e32 v50, 16, v206
	v_and_b32_e32 v51, 0xffff0000, v206
	v_lshlrev_b32_e32 v56, 16, v209
	v_and_b32_e32 v57, 0xffff0000, v209
	v_lshl_add_u64 v[54:55], s[60:61], 1, v[54:55]
	v_pk_fma_f32 v[46:47], v[46:47], 0.5, v[50:51] op_sel_hi:[1,0,1]
	v_pk_fma_f32 v[50:51], v[44:45], 0.5, v[56:57] op_sel_hi:[1,0,1]
	v_lshl_add_u64 v[54:55], v[54:55], 0, s[18:19]
	v_cvt_pk_bf16_f32 v42, v46, v47
	v_cvt_pk_bf16_f32 v43, v48, v49
	v_cvt_pk_bf16_f32 v44, v52, v53
	v_cvt_pk_bf16_f32 v45, v50, v51
	v_lshl_add_u64 v[54:55], v[54:55], 0, v[0:1]
	global_store_dwordx4 v[54:55], v[42:45], off
	s_nop 1
	v_mul_f32_e32 v42, v47, v47
	v_mul_f32_e32 v43, v49, v49
	v_fmac_f32_e32 v42, v46, v46
	v_fmac_f32_e32 v43, v48, v48
	v_add_f32_e32 v42, v42, v43
	v_mul_f32_e32 v43, v53, v53
	v_fmac_f32_e32 v43, v52, v52
	v_add_f32_e32 v42, v43, v42
	v_mul_f32_e32 v43, v51, v51
	v_fmac_f32_e32 v43, v50, v50
	v_add_f32_e32 v50, v43, v42
	v_lshlrev_b32_e32 v42, 16, v210
	v_and_b32_e32 v43, 0xffff0000, v210
	v_lshlrev_b32_e32 v44, 16, v211
	v_and_b32_e32 v45, 0xffff0000, v211
	v_lshlrev_b32_e32 v46, 16, v212
	v_and_b32_e32 v47, 0xffff0000, v212
	v_lshlrev_b32_e32 v48, 16, v213
	v_and_b32_e32 v49, 0xffff0000, v213
	v_pk_fma_f32 v[40:41], v[40:41], 0.5, v[44:45] op_sel_hi:[1,0,1]
	v_pk_fma_f32 v[38:39], v[38:39], 0.5, v[42:43] op_sel_hi:[1,0,1]
	v_pk_fma_f32 v[42:43], v[36:37], 0.5, v[48:49] op_sel_hi:[1,0,1]
	v_pk_fma_f32 v[44:45], v[34:35], 0.5, v[46:47] op_sel_hi:[1,0,1]
	v_cvt_pk_bf16_f32 v34, v38, v39
	v_cvt_pk_bf16_f32 v35, v40, v41
	v_cvt_pk_bf16_f32 v36, v44, v45
	v_cvt_pk_bf16_f32 v37, v42, v43
	global_store_dwordx4 v[54:55], v[34:37], off offset:256
	s_nop 1
	v_mul_f32_e32 v34, v39, v39
	v_mul_f32_e32 v35, v41, v41
	v_fmac_f32_e32 v34, v38, v38
	v_fmac_f32_e32 v35, v40, v40
	v_add_f32_e32 v34, v34, v35
	v_mul_f32_e32 v35, v45, v45
	v_fmac_f32_e32 v35, v44, v44
	v_add_f32_e32 v34, v35, v34
	v_mul_f32_e32 v35, v43, v43
	v_fmac_f32_e32 v35, v42, v42
	v_add_f32_e32 v34, v35, v34
	v_add_f32_e32 v34, v50, v34
	v_mov_b32_e32 v35, v34
	s_nop 1
	v_permlane32_swap_b32_e32 v34, v35
	v_add_f32_e32 v34, v34, v35
	v_mov_b32_e32 v35, v34
	s_nop 1
	v_permlane16_swap_b32_e32 v34, v35
	s_and_saveexec_b64 s[62:63], vcc
	s_cbranch_execz .LBB0_622
	v_lshlrev_b64 v[36:37], 6, v[98:99]
	v_lshl_add_u64 v[36:37], s[12:13], 0, v[36:37]
	v_lshl_add_u64 v[36:37], s[58:59], 2, v[36:37]
	s_lshl_b32 s76, s45, 2
	s_mov_b32 s77, s19
	v_lshl_add_u64 v[36:37], v[36:37], 0, s[76:77]
	v_add_f32_e32 v34, v34, v35
	global_store_dword v[36:37], v34, off
; __device__ __forceinline__ u32x4 pack8(f32x4 a, f32x4 b) { u32x4 w; w.x = cvtpk(a[0], a[1]); w.y = cvtpk(a[2], a[3]); w.z = cvtpk(b[0], b[1]); w.w = cvtpk(b[2], b[3]); return w; }
;     __device__ __forceinline__ void operator()(AccRef acc, const Unit& u, int wr, int wc, int fr, int fq) const {
;     ...
;             for (int m = 0; m < 4; ++m) {
;                 const int row = u.pm * 256 + ai * 128 + wr * 64 + m * 16 + fr; float part = 0.f;
;                 const float sc = RS ? scale * rst[u.ui * 256 + ai * 128 + wr * 64 + m * 16 + fr] : scale;
; #pragma unroll
;                 for (int bj = 0; bj < 2; ++bj) {
;                     const size_t idx = (size_t)row * D + u.pn * 256 + bj * 128 + wc * 32 + 8 * fq;
;                     const u32x4 o4 = ow[m][bj];
;                     f32x4 v0, v1;
;                     v0[0] = __uint_as_float(o4.x << 16); v0[1] = __uint_as_float(o4.x & 0xffff0000u); v0[2] = __uint_as_float(o4.y << 16); v0[3] = __uint_as_float(o4.y & 0xffff0000u);
;                     v1[0] = __uint_as_float(o4.z << 16); v1[1] = __uint_as_float(o4.z & 0xffff0000u); v1[2] = __uint_as_float(o4.w << 16); v1[3] = __uint_as_float(o4.w & 0xffff0000u);
;                     v0 = v0 + acc[ai][bj][m][0] * sc; v1 = v1 + acc[ai][bj][m][1] * sc;
;                     *(u32x4*)(hb + idx) = pack8(v0, v1);
;                     part += (v0[0] * v0[0] + v0[1] * v0[1]) + (v0[2] * v0[2] + v0[3] * v0[3]) + (v1[0] * v1[0] + v1[1] * v1[1]) + (v1[2] * v1[2] + v1[3] * v1[3]);
;                 }
;                 part = fq_sum(part);
;                 if (fq == 0) ssn[(size_t)row * 16 + u.pn * 4 + wc] = part;
.LBB0_622:
	s_or_b64 exec, exec, s[62:63]
	v_lshlrev_b32_e32 v36, 16, v239
	v_and_b32_e32 v37, 0xffff0000, v239
	v_lshlrev_b32_e32 v38, 16, v240
	v_and_b32_e32 v39, 0xffff0000, v240
	v_pk_fma_f32 v[32:33], v[32:33], 0.5, v[36:37] op_sel_hi:[1,0,1]
	v_pk_fma_f32 v[36:37], v[26:27], 0.5, v[38:39] op_sel_hi:[1,0,1]
	v_lshl_add_u64 v[38:39], s[10:11], 0, v[96:97]
	v_lshlrev_b32_e32 v34, 16, v238
	v_and_b32_e32 v35, 0xffff0000, v238
	v_lshlrev_b32_e32 v40, 16, v241
	v_and_b32_e32 v41, 0xffff0000, v241
	v_lshl_add_u64 v[38:39], s[60:61], 1, v[38:39]
	v_pk_fma_f32 v[30:31], v[30:31], 0.5, v[34:35] op_sel_hi:[1,0,1]
	v_pk_fma_f32 v[34:35], v[28:29], 0.5, v[40:41] op_sel_hi:[1,0,1]
	v_lshl_add_u64 v[38:39], v[38:39], 0, s[18:19]
	v_cvt_pk_bf16_f32 v26, v30, v31
	v_cvt_pk_bf16_f32 v27, v32, v33
	v_cvt_pk_bf16_f32 v28, v36, v37
	v_cvt_pk_bf16_f32 v29, v34, v35
	v_lshl_add_u64 v[38:39], v[38:39], 0, v[0:1]
	global_store_dwordx4 v[38:39], v[26:29], off
	s_nop 1
	v_mul_f32_e32 v26, v31, v31
	v_mul_f32_e32 v27, v33, v33
	v_fmac_f32_e32 v26, v30, v30
	v_fmac_f32_e32 v27, v32, v32
	v_add_f32_e32 v26, v26, v27
	v_mul_f32_e32 v27, v37, v37
	v_fmac_f32_e32 v27, v36, v36
	v_add_f32_e32 v26, v27, v26
	v_mul_f32_e32 v27, v35, v35
	v_fmac_f32_e32 v27, v34, v34
	v_add_f32_e32 v34, v27, v26
	v_lshlrev_b32_e32 v26, 16, v242
	v_and_b32_e32 v27, 0xffff0000, v242
	v_lshlrev_b32_e32 v28, 16, v243
	v_and_b32_e32 v29, 0xffff0000, v243
	v_lshlrev_b32_e32 v30, 16, v244
	v_and_b32_e32 v31, 0xffff0000, v244
	v_lshlrev_b32_e32 v32, 16, v245
	v_and_b32_e32 v33, 0xffff0000, v245
	v_pk_fma_f32 v[24:25], v[24:25], 0.5, v[28:29] op_sel_hi:[1,0,1]
	v_pk_fma_f32 v[22:23], v[22:23], 0.5, v[26:27] op_sel_hi:[1,0,1]
	v_pk_fma_f32 v[26:27], v[20:21], 0.5, v[32:33] op_sel_hi:[1,0,1]
	v_pk_fma_f32 v[28:29], v[18:19], 0.5, v[30:31] op_sel_hi:[1,0,1]
	v_cvt_pk_bf16_f32 v18, v22, v23
	v_cvt_pk_bf16_f32 v19, v24, v25
	v_cvt_pk_bf16_f32 v20, v28, v29
	v_cvt_pk_bf16_f32 v21, v26, v27
	global_store_dwordx4 v[38:39], v[18:21], off offset:256
	s_nop 1
	v_mul_f32_e32 v18, v23, v23
	v_mul_f32_e32 v19, v25, v25
	v_fmac_f32_e32 v18, v22, v22
	v_fmac_f32_e32 v19, v24, v24
	v_add_f32_e32 v18, v18, v19
	v_mul_f32_e32 v19, v29, v29
	v_fmac_f32_e32 v19, v28, v28
	v_add_f32_e32 v18, v19, v18
	v_mul_f32_e32 v19, v27, v27
	v_fmac_f32_e32 v19, v26, v26
	v_add_f32_e32 v18, v19, v18
	v_add_f32_e32 v18, v34, v18
	v_mov_b32_e32 v19, v18
	s_nop 1
	v_permlane32_swap_b32_e32 v18, v19
	v_add_f32_e32 v18, v18, v19
	v_mov_b32_e32 v19, v18
	s_nop 1
	v_permlane16_swap_b32_e32 v18, v19
	s_and_saveexec_b64 s[62:63], vcc
	s_cbranch_execz .LBB0_624
	v_lshlrev_b64 v[20:21], 6, v[94:95]
	v_lshl_add_u64 v[20:21], s[12:13], 0, v[20:21]
	v_lshl_add_u64 v[20:21], s[58:59], 2, v[20:21]
	s_lshl_b32 s76, s45, 2
	s_mov_b32 s77, s19
	v_lshl_add_u64 v[20:21], v[20:21], 0, s[76:77]
	v_add_f32_e32 v18, v18, v19
	global_store_dword v[20:21], v18, off
.LBB0_624:
	s_or_b64 exec, exec, s[62:63]
	v_lshlrev_b32_e32 v20, 16, v247
	v_and_b32_e32 v21, 0xffff0000, v247
	v_lshlrev_b32_e32 v22, 16, v248
	v_and_b32_e32 v23, 0xffff0000, v248
	v_pk_fma_f32 v[16:17], v[16:17], 0.5, v[20:21] op_sel_hi:[1,0,1]
	v_pk_fma_f32 v[20:21], v[10:11], 0.5, v[22:23] op_sel_hi:[1,0,1]
	v_lshl_add_u64 v[22:23], s[10:11], 0, v[92:93]
	v_lshlrev_b32_e32 v18, 16, v246
	v_and_b32_e32 v19, 0xffff0000, v246
	v_lshlrev_b32_e32 v24, 16, v249
	v_and_b32_e32 v25, 0xffff0000, v249
	v_lshl_add_u64 v[22:23], s[60:61], 1, v[22:23]
	v_pk_fma_f32 v[14:15], v[14:15], 0.5, v[18:19] op_sel_hi:[1,0,1]
	v_pk_fma_f32 v[18:19], v[12:13], 0.5, v[24:25] op_sel_hi:[1,0,1]
	v_lshl_add_u64 v[22:23], v[22:23], 0, s[18:19]
	v_cvt_pk_bf16_f32 v10, v14, v15
	v_cvt_pk_bf16_f32 v11, v16, v17
	v_cvt_pk_bf16_f32 v12, v20, v21
	v_cvt_pk_bf16_f32 v13, v18, v19
	v_lshl_add_u64 v[22:23], v[22:23], 0, v[0:1]
	global_store_dwordx4 v[22:23], v[10:13], off
	v_mul_f32_e32 v0, v15, v15
	v_fmac_f32_e32 v0, v14, v14
	v_mul_f32_e32 v10, v17, v17
	v_fmac_f32_e32 v10, v16, v16
	v_add_f32_e32 v0, v0, v10
	v_mul_f32_e32 v10, v21, v21
	v_fmac_f32_e32 v10, v20, v20
	v_add_f32_e32 v0, v10, v0
	v_mul_f32_e32 v10, v19, v19
	v_fmac_f32_e32 v10, v18, v18
	v_add_f32_e32 v0, v10, v0
	v_lshlrev_b32_e32 v10, 16, v250
	v_and_b32_e32 v11, 0xffff0000, v250
	v_lshlrev_b32_e32 v12, 16, v251
	v_and_b32_e32 v13, 0xffff0000, v251
	v_lshlrev_b32_e32 v14, 16, v252
	v_and_b32_e32 v15, 0xffff0000, v252
	v_lshlrev_b32_e32 v16, 16, v253
	v_and_b32_e32 v17, 0xffff0000, v253
	v_pk_fma_f32 v[8:9], v[8:9], 0.5, v[12:13] op_sel_hi:[1,0,1]
	v_pk_fma_f32 v[6:7], v[6:7], 0.5, v[10:11] op_sel_hi:[1,0,1]
	v_pk_fma_f32 v[10:11], v[4:5], 0.5, v[16:17] op_sel_hi:[1,0,1]
	v_pk_fma_f32 v[12:13], v[2:3], 0.5, v[14:15] op_sel_hi:[1,0,1]
	v_cvt_pk_bf16_f32 v2, v6, v7
	v_cvt_pk_bf16_f32 v3, v8, v9
	v_cvt_pk_bf16_f32 v4, v12, v13
	v_cvt_pk_bf16_f32 v5, v10, v11
	global_store_dwordx4 v[22:23], v[2:5], off offset:256
	s_nop 1
	v_mul_f32_e32 v2, v7, v7
	v_mul_f32_e32 v3, v9, v9
	v_fmac_f32_e32 v2, v6, v6
	v_fmac_f32_e32 v3, v8, v8
	v_add_f32_e32 v2, v2, v3
	v_mul_f32_e32 v3, v13, v13
	v_fmac_f32_e32 v3, v12, v12
	v_add_f32_e32 v2, v3, v2
	v_mul_f32_e32 v3, v11, v11
	v_fmac_f32_e32 v3, v10, v10
	v_add_f32_e32 v2, v3, v2
	v_add_f32_e32 v0, v0, v2
	v_mov_b32_e32 v2, v0
	s_nop 1
	v_permlane32_swap_b32_e32 v0, v2
	v_add_f32_e32 v0, v0, v2
	v_mov_b32_e32 v2, v0
	s_nop 1
	v_permlane16_swap_b32_e32 v0, v2
	s_and_saveexec_b64 s[60:61], vcc
	s_cbranch_execz .LBB0_626
	v_lshlrev_b64 v[4:5], 6, v[90:91]
	v_lshl_add_u64 v[4:5], s[12:13], 0, v[4:5]
	v_lshl_add_u64 v[4:5], s[58:59], 2, v[4:5]
	s_lshl_b32 s18, s45, 2
	v_lshl_add_u64 v[4:5], v[4:5], 0, s[18:19]
	v_add_f32_e32 v0, v0, v2
	global_store_dword v[4:5], v0, off

; __device__ __forceinline__ u32x4 pack8(f32x4 a, f32x4 b) { u32x4 w; w.x = cvtpk(a[0], a[1]); w.y = cvtpk(a[2], a[3]); w.z = cvtpk(b[0], b[1]); w.w = cvtpk(b[2], b[3]); return w; }
;     __device__ __forceinline__ void operator()(AccRef acc, const Unit& u, int wr, int wc, int fr, int fq) const {
;     ...
;             for (int m = 0; m < 4; ++m) {
;                 const int row = u.pm * 256 + ai * 128 + wr * 64 + m * 16 + fr; float part = 0.f;
;                 const float sc = RS ? scale * rst[u.ui * 256 + ai * 128 + wr * 64 + m * 16 + fr] : scale;
; #pragma unroll
;                 for (int bj = 0; bj < 2; ++bj) {
;                     const size_t idx = (size_t)row * D + u.pn * 256 + bj * 128 + wc * 32 + 8 * fq;
;                     const u32x4 o4 = ow[m][bj];
;                     f32x4 v0, v1;
;                     v0[0] = __uint_as_float(o4.x << 16); v0[1] = __uint_as_float(o4.x & 0xffff0000u); v0[2] = __uint_as_float(o4.y << 16); v0[3] = __uint_as_float(o4.y & 0xffff0000u);
;                     v1[0] = __uint_as_float(o4.z << 16); v1[1] = __uint_as_float(o4.z & 0xffff0000u); v1[2] = __uint_as_float(o4.w << 16); v1[3] = __uint_as_float(o4.w & 0xffff0000u);
;                     v0 = v0 + acc[ai][bj][m][0] * sc; v1 = v1 + acc[ai][bj][m][1] * sc;
;                     *(u32x4*)(hb + idx) = pack8(v0, v1);
;                     part += (v0[0] * v0[0] + v0[1] * v0[1]) + (v0[2] * v0[2] + v0[3] * v0[3]) + (v1[0] * v1[0] + v1[1] * v1[1]) + (v1[2] * v1[2] + v1[3] * v1[3]);
;                 }
;                 part = fq_sum(part);
;                 if (fq == 0) ssn[(size_t)row * 16 + u.pn * 4 + wc] = part;
.LBB0_1903:
	s_or_b64 exec, exec, s[58:59]
	v_add_u32_e32 v102, 0x80, v154
	v_ashrrev_i32_e32 v103, 31, v102
	v_add_u32_e32 v98, 0x90, v154
	v_lshlrev_b64 v[112:113], 11, v[102:103]
	v_ashrrev_i32_e32 v99, 31, v98
	v_add_u32_e32 v94, 0xa0, v154
	v_lshl_add_u64 v[66:67], v[156:157], 0, v[112:113]
	v_lshlrev_b64 v[100:101], 11, v[98:99]
	v_ashrrev_i32_e32 v95, 31, v94
	v_add_u32_e32 v90, 0xb0, v154
	v_lshl_add_u64 v[66:67], v[156:157], 0, v[100:101]
	v_lshlrev_b64 v[96:97], 11, v[94:95]
	v_ashrrev_i32_e32 v91, 31, v90
	v_lshl_add_u64 v[66:67], v[156:157], 0, v[96:97]
	v_lshlrev_b64 v[92:93], 11, v[90:91]
	v_lshl_add_u64 v[66:67], v[156:157], 0, v[92:93]
	s_nop 0
	v_lshl_add_u64 v[112:113], s[10:11], 0, v[112:113]
	v_lshlrev_b32_e32 v114, 16, v186
	v_and_b32_e32 v115, 0xffff0000, v186
	v_lshlrev_b32_e32 v104, 16, v187
	v_and_b32_e32 v105, 0xffff0000, v187
	v_lshlrev_b32_e32 v116, 16, v188
	v_and_b32_e32 v117, 0xffff0000, v188
	v_lshlrev_b32_e32 v106, 16, v189
	v_and_b32_e32 v107, 0xffff0000, v189
	v_lshl_add_u64 v[112:113], s[56:57], 1, v[112:113]
	v_pk_add_f32 v[64:65], v[64:65], v[104:105]
	v_pk_add_f32 v[62:63], v[62:63], v[114:115]
	v_pk_add_f32 v[104:105], v[60:61], v[106:107]
	v_pk_add_f32 v[106:107], v[58:59], v[116:117]
	v_lshl_add_u64 v[112:113], v[112:113], 0, s[18:19]
	v_cvt_pk_bf16_f32 v58, v62, v63
	v_cvt_pk_bf16_f32 v59, v64, v65
	v_cvt_pk_bf16_f32 v60, v106, v107
	v_cvt_pk_bf16_f32 v61, v104, v105
	v_lshl_add_u64 v[112:113], v[112:113], 0, v[0:1]
	global_store_dwordx4 v[112:113], v[58:61], off
	s_nop 1
	v_mul_f32_e32 v58, v63, v63
	v_mul_f32_e32 v59, v65, v65
	v_fmac_f32_e32 v58, v62, v62
	v_fmac_f32_e32 v59, v64, v64
	v_add_f32_e32 v58, v58, v59
	v_mul_f32_e32 v59, v107, v107
	v_fmac_f32_e32 v59, v106, v106
	v_add_f32_e32 v58, v59, v58
	v_mul_f32_e32 v59, v105, v105
	v_fmac_f32_e32 v59, v104, v104
	v_add_f32_e32 v104, v59, v58
	v_lshlrev_b32_e32 v58, 16, v196
	v_and_b32_e32 v59, 0xffff0000, v196
	v_lshlrev_b32_e32 v60, 16, v197
	v_and_b32_e32 v61, 0xffff0000, v197
	v_lshlrev_b32_e32 v62, 16, v198
	v_and_b32_e32 v63, 0xffff0000, v198
	v_lshlrev_b32_e32 v64, 16, v199
	v_and_b32_e32 v65, 0xffff0000, v199
	v_pk_add_f32 v[56:57], v[56:57], v[60:61]
	v_pk_add_f32 v[54:55], v[54:55], v[58:59]
	v_pk_add_f32 v[58:59], v[52:53], v[64:65]
	v_pk_add_f32 v[60:61], v[50:51], v[62:63]
	v_cvt_pk_bf16_f32 v50, v54, v55
	v_cvt_pk_bf16_f32 v51, v56, v57
	v_cvt_pk_bf16_f32 v52, v60, v61
	v_cvt_pk_bf16_f32 v53, v58, v59
	global_store_dwordx4 v[112:113], v[50:53], off offset:256
	s_nop 1
	v_mul_f32_e32 v50, v55, v55
	v_mul_f32_e32 v51, v57, v57
	v_fmac_f32_e32 v50, v54, v54
	v_fmac_f32_e32 v51, v56, v56
	v_add_f32_e32 v50, v50, v51
	v_mul_f32_e32 v51, v61, v61
	v_fmac_f32_e32 v51, v60, v60
	v_add_f32_e32 v50, v51, v50
	v_mul_f32_e32 v51, v59, v59
	v_fmac_f32_e32 v51, v58, v58
	v_add_f32_e32 v50, v51, v50
	v_add_f32_e32 v50, v104, v50
	v_mov_b32_e32 v51, v50
	s_nop 1
	v_permlane32_swap_b32_e32 v50, v51
	v_add_f32_e32 v50, v50, v51
	v_mov_b32_e32 v51, v50
	s_nop 1
	v_permlane16_swap_b32_e32 v50, v51
	s_and_saveexec_b64 s[58:59], vcc
	s_cbranch_execz .LBB0_1905
	v_lshlrev_b64 v[52:53], 6, v[102:103]
	v_lshl_add_u64 v[52:53], s[12:13], 0, v[52:53]
	v_lshl_add_u64 v[52:53], s[54:55], 2, v[52:53]
	s_lshl_b32 s72, s45, 2
	s_mov_b32 s73, s19
	v_lshl_add_u64 v[52:53], v[52:53], 0, s[72:73]
	v_add_f32_e32 v50, v50, v51
	global_store_dword v[52:53], v50, off
.LBB0_1905:
	s_or_b64 exec, exec, s[58:59]
	v_lshlrev_b32_e32 v52, 16, v201
	v_and_b32_e32 v53, 0xffff0000, v201
	v_lshlrev_b32_e32 v54, 16, v202
	v_and_b32_e32 v55, 0xffff0000, v202
	v_pk_add_f32 v[48:49], v[48:49], v[52:53]
	v_pk_add_f32 v[52:53], v[42:43], v[54:55]
	v_lshl_add_u64 v[54:55], s[10:11], 0, v[100:101]
	v_lshlrev_b32_e32 v50, 16, v200
	v_and_b32_e32 v51, 0xffff0000, v200
	v_lshlrev_b32_e32 v56, 16, v203
	v_and_b32_e32 v57, 0xffff0000, v203
	v_lshl_add_u64 v[54:55], s[56:57], 1, v[54:55]
	v_pk_add_f32 v[46:47], v[46:47], v[50:51]
	v_pk_add_f32 v[50:51], v[44:45], v[56:57]
	v_lshl_add_u64 v[54:55], v[54:55], 0, s[18:19]
	v_cvt_pk_bf16_f32 v42, v46, v47
	v_cvt_pk_bf16_f32 v43, v48, v49
	v_cvt_pk_bf16_f32 v44, v52, v53
	v_cvt_pk_bf16_f32 v45, v50, v51
	v_lshl_add_u64 v[54:55], v[54:55], 0, v[0:1]
	global_store_dwordx4 v[54:55], v[42:45], off
	s_nop 1
	v_mul_f32_e32 v42, v47, v47
	v_mul_f32_e32 v43, v49, v49
	v_fmac_f32_e32 v42, v46, v46
	v_fmac_f32_e32 v43, v48, v48
	v_add_f32_e32 v42, v42, v43
	v_mul_f32_e32 v43, v53, v53
	v_fmac_f32_e32 v43, v52, v52
	v_add_f32_e32 v42, v43, v42
	v_mul_f32_e32 v43, v51, v51
	v_fmac_f32_e32 v43, v50, v50
	v_add_f32_e32 v50, v43, v42
	v_lshlrev_b32_e32 v42, 16, v204
	v_and_b32_e32 v43, 0xffff0000, v204
	v_lshlrev_b32_e32 v44, 16, v205
	v_and_b32_e32 v45, 0xffff0000, v205
	v_lshlrev_b32_e32 v46, 16, v206
	v_and_b32_e32 v47, 0xffff0000, v206
	v_lshlrev_b32_e32 v48, 16, v207
	v_and_b32_e32 v49, 0xffff0000, v207
	v_pk_add_f32 v[40:41], v[40:41], v[44:45]
	v_pk_add_f32 v[38:39], v[38:39], v[42:43]
	v_pk_add_f32 v[42:43], v[36:37], v[48:49]
	v_pk_add_f32 v[44:45], v[34:35], v[46:47]
	v_cvt_pk_bf16_f32 v34, v38, v39
	v_cvt_pk_bf16_f32 v35, v40, v41
	v_cvt_pk_bf16_f32 v36, v44, v45
	v_cvt_pk_bf16_f32 v37, v42, v43
	global_store_dwordx4 v[54:55], v[34:37], off offset:256
	s_nop 1
	v_mul_f32_e32 v34, v39, v39
	v_mul_f32_e32 v35, v41, v41
	v_fmac_f32_e32 v34, v38, v38
	v_fmac_f32_e32 v35, v40, v40
	v_add_f32_e32 v34, v34, v35
	v_mul_f32_e32 v35, v45, v45
	v_fmac_f32_e32 v35, v44, v44
	v_add_f32_e32 v34, v35, v34
	v_mul_f32_e32 v35, v43, v43
	v_fmac_f32_e32 v35, v42, v42
	v_add_f32_e32 v34, v35, v34
	v_add_f32_e32 v34, v50, v34
	v_mov_b32_e32 v35, v34
	s_nop 1
	v_permlane32_swap_b32_e32 v34, v35
	v_add_f32_e32 v34, v34, v35
	v_mov_b32_e32 v35, v34
	s_nop 1
	v_permlane16_swap_b32_e32 v34, v35
	s_and_saveexec_b64 s[58:59], vcc
	s_cbranch_execz .LBB0_1907
	v_lshlrev_b64 v[36:37], 6, v[98:99]
	v_lshl_add_u64 v[36:37], s[12:13], 0, v[36:37]
	v_lshl_add_u64 v[36:37], s[54:55], 2, v[36:37]
	s_lshl_b32 s72, s45, 2
	s_mov_b32 s73, s19
	v_lshl_add_u64 v[36:37], v[36:37], 0, s[72:73]
	v_add_f32_e32 v34, v34, v35
	global_store_dword v[36:37], v34, off
; __device__ __forceinline__ u32x4 pack8(f32x4 a, f32x4 b) { u32x4 w; w.x = cvtpk(a[0], a[1]); w.y = cvtpk(a[2], a[3]); w.z = cvtpk(b[0], b[1]); w.w = cvtpk(b[2], b[3]); return w; }
;     __device__ __forceinline__ void operator()(AccRef acc, const Unit& u, int wr, int wc, int fr, int fq) const {
;     ...
;             for (int m = 0; m < 4; ++m) {
;                 const int row = u.pm * 256 + ai * 128 + wr * 64 + m * 16 + fr; float part = 0.f;
;                 const float sc = RS ? scale * rst[u.ui * 256 + ai * 128 + wr * 64 + m * 16 + fr] : scale;
; #pragma unroll
;                 for (int bj = 0; bj < 2; ++bj) {
;                     const size_t idx = (size_t)row * D + u.pn * 256 + bj * 128 + wc * 32 + 8 * fq;
;                     const u32x4 o4 = ow[m][bj];
;                     f32x4 v0, v1;
;                     v0[0] = __uint_as_float(o4.x << 16); v0[1] = __uint_as_float(o4.x & 0xffff0000u); v0[2] = __uint_as_float(o4.y << 16); v0[3] = __uint_as_float(o4.y & 0xffff0000u);
;                     v1[0] = __uint_as_float(o4.z << 16); v1[1] = __uint_as_float(o4.z & 0xffff0000u); v1[2] = __uint_as_float(o4.w << 16); v1[3] = __uint_as_float(o4.w & 0xffff0000u);
;                     v0 = v0 + acc[ai][bj][m][0] * sc; v1 = v1 + acc[ai][bj][m][1] * sc;
;                     *(u32x4*)(hb + idx) = pack8(v0, v1);
;                     part += (v0[0] * v0[0] + v0[1] * v0[1]) + (v0[2] * v0[2] + v0[3] * v0[3]) + (v1[0] * v1[0] + v1[1] * v1[1]) + (v1[2] * v1[2] + v1[3] * v1[3]);
;                 }
;                 part = fq_sum(part);
;                 if (fq == 0) ssn[(size_t)row * 16 + u.pn * 4 + wc] = part;
;             }
.LBB0_1907:
	s_or_b64 exec, exec, s[58:59]
	v_lshlrev_b32_e32 v36, 16, v209
	v_and_b32_e32 v37, 0xffff0000, v209
	v_lshlrev_b32_e32 v38, 16, v210
	v_and_b32_e32 v39, 0xffff0000, v210
	v_pk_add_f32 v[32:33], v[32:33], v[36:37]
	v_pk_add_f32 v[36:37], v[26:27], v[38:39]
	v_lshl_add_u64 v[38:39], s[10:11], 0, v[96:97]
	v_lshlrev_b32_e32 v34, 16, v208
	v_and_b32_e32 v35, 0xffff0000, v208
	v_lshlrev_b32_e32 v40, 16, v211
	v_and_b32_e32 v41, 0xffff0000, v211
	v_lshl_add_u64 v[38:39], s[56:57], 1, v[38:39]
	v_pk_add_f32 v[30:31], v[30:31], v[34:35]
	v_pk_add_f32 v[34:35], v[28:29], v[40:41]
	v_lshl_add_u64 v[38:39], v[38:39], 0, s[18:19]
	v_cvt_pk_bf16_f32 v26, v30, v31
	v_cvt_pk_bf16_f32 v27, v32, v33
	v_cvt_pk_bf16_f32 v28, v36, v37
	v_cvt_pk_bf16_f32 v29, v34, v35
	v_lshl_add_u64 v[38:39], v[38:39], 0, v[0:1]
	global_store_dwordx4 v[38:39], v[26:29], off
	s_nop 1
	v_mul_f32_e32 v26, v31, v31
	v_mul_f32_e32 v27, v33, v33
	v_fmac_f32_e32 v26, v30, v30
	v_fmac_f32_e32 v27, v32, v32
	v_add_f32_e32 v26, v26, v27
	v_mul_f32_e32 v27, v37, v37
	v_fmac_f32_e32 v27, v36, v36
	v_add_f32_e32 v26, v27, v26
	v_mul_f32_e32 v27, v35, v35
	v_fmac_f32_e32 v27, v34, v34
	v_add_f32_e32 v34, v27, v26
	v_lshlrev_b32_e32 v26, 16, v212
	v_and_b32_e32 v27, 0xffff0000, v212
	v_lshlrev_b32_e32 v28, 16, v213
	v_and_b32_e32 v29, 0xffff0000, v213
	v_lshlrev_b32_e32 v30, 16, v214
	v_and_b32_e32 v31, 0xffff0000, v214
	v_lshlrev_b32_e32 v32, 16, v215
	v_and_b32_e32 v33, 0xffff0000, v215
	v_pk_add_f32 v[24:25], v[24:25], v[28:29]
	v_pk_add_f32 v[22:23], v[22:23], v[26:27]
	v_pk_add_f32 v[26:27], v[20:21], v[32:33]
	v_pk_add_f32 v[28:29], v[18:19], v[30:31]
	v_cvt_pk_bf16_f32 v18, v22, v23
	v_cvt_pk_bf16_f32 v19, v24, v25
	v_cvt_pk_bf16_f32 v20, v28, v29
	v_cvt_pk_bf16_f32 v21, v26, v27
	global_store_dwordx4 v[38:39], v[18:21], off offset:256
	s_nop 1
	v_mul_f32_e32 v18, v23, v23
	v_mul_f32_e32 v19, v25, v25
	v_fmac_f32_e32 v18, v22, v22
	v_fmac_f32_e32 v19, v24, v24
	v_add_f32_e32 v18, v18, v19
	v_mul_f32_e32 v19, v29, v29
	v_fmac_f32_e32 v19, v28, v28
	v_add_f32_e32 v18, v19, v18
	v_mul_f32_e32 v19, v27, v27
	v_fmac_f32_e32 v19, v26, v26
	v_add_f32_e32 v18, v19, v18
	v_add_f32_e32 v18, v34, v18
	v_mov_b32_e32 v19, v18
	s_nop 1
	v_permlane32_swap_b32_e32 v18, v19
	v_add_f32_e32 v18, v18, v19
	v_mov_b32_e32 v19, v18
	s_nop 1
	v_permlane16_swap_b32_e32 v18, v19
	s_and_saveexec_b64 s[58:59], vcc
	s_cbranch_execz .LBB0_1909
	v_lshlrev_b64 v[20:21], 6, v[94:95]
	v_lshl_add_u64 v[20:21], s[12:13], 0, v[20:21]
	v_lshl_add_u64 v[20:21], s[54:55], 2, v[20:21]
	s_lshl_b32 s72, s45, 2
	s_mov_b32 s73, s19
	v_lshl_add_u64 v[20:21], v[20:21], 0, s[72:73]
	v_add_f32_e32 v18, v18, v19
	global_store_dword v[20:21], v18, off
.LBB0_1909:
	s_or_b64 exec, exec, s[58:59]
	v_lshlrev_b32_e32 v20, 16, v221
	v_and_b32_e32 v21, 0xffff0000, v221
	v_lshlrev_b32_e32 v22, 16, v222
	v_and_b32_e32 v23, 0xffff0000, v222
	v_pk_add_f32 v[16:17], v[16:17], v[20:21]
	v_pk_add_f32 v[20:21], v[10:11], v[22:23]
	v_lshl_add_u64 v[22:23], s[10:11], 0, v[92:93]
	v_lshlrev_b32_e32 v18, 16, v220
	v_and_b32_e32 v19, 0xffff0000, v220
	v_lshlrev_b32_e32 v24, 16, v223
	v_and_b32_e32 v25, 0xffff0000, v223
	v_lshl_add_u64 v[22:23], s[56:57], 1, v[22:23]
	v_pk_add_f32 v[14:15], v[14:15], v[18:19]
	v_pk_add_f32 v[18:19], v[12:13], v[24:25]
	v_lshl_add_u64 v[22:23], v[22:23], 0, s[18:19]
	v_cvt_pk_bf16_f32 v10, v14, v15
	v_cvt_pk_bf16_f32 v11, v16, v17
	v_cvt_pk_bf16_f32 v12, v20, v21
	v_cvt_pk_bf16_f32 v13, v18, v19
	v_lshl_add_u64 v[22:23], v[22:23], 0, v[0:1]
	global_store_dwordx4 v[22:23], v[10:13], off
	v_mul_f32_e32 v0, v15, v15
	v_fmac_f32_e32 v0, v14, v14
	v_mul_f32_e32 v10, v17, v17
	v_fmac_f32_e32 v10, v16, v16
	v_add_f32_e32 v0, v0, v10
	v_mul_f32_e32 v10, v21, v21
	v_fmac_f32_e32 v10, v20, v20
	v_add_f32_e32 v0, v10, v0
	v_mul_f32_e32 v10, v19, v19
	v_fmac_f32_e32 v10, v18, v18
	v_add_f32_e32 v0, v10, v0
	v_lshlrev_b32_e32 v10, 16, v238
	v_and_b32_e32 v11, 0xffff0000, v238
	v_lshlrev_b32_e32 v12, 16, v239
	v_and_b32_e32 v13, 0xffff0000, v239
	v_lshlrev_b32_e32 v14, 16, v240
	v_and_b32_e32 v15, 0xffff0000, v240
	v_lshlrev_b32_e32 v16, 16, v241
	v_and_b32_e32 v17, 0xffff0000, v241
	v_pk_add_f32 v[8:9], v[8:9], v[12:13]
	v_pk_add_f32 v[6:7], v[6:7], v[10:11]
	v_pk_add_f32 v[10:11], v[4:5], v[16:17]
	v_pk_add_f32 v[12:13], v[2:3], v[14:15]
	v_cvt_pk_bf16_f32 v2, v6, v7
	v_cvt_pk_bf16_f32 v3, v8, v9
	v_cvt_pk_bf16_f32 v4, v12, v13
	v_cvt_pk_bf16_f32 v5, v10, v11
	global_store_dwordx4 v[22:23], v[2:5], off offset:256
	s_nop 1
	v_mul_f32_e32 v2, v7, v7
	v_mul_f32_e32 v3, v9, v9
	v_fmac_f32_e32 v2, v6, v6
	v_fmac_f32_e32 v3, v8, v8
	v_add_f32_e32 v2, v2, v3
	v_mul_f32_e32 v3, v13, v13
	v_fmac_f32_e32 v3, v12, v12
	v_add_f32_e32 v2, v3, v2
	v_mul_f32_e32 v3, v11, v11
	v_fmac_f32_e32 v3, v10, v10
	v_add_f32_e32 v2, v3, v2
	v_add_f32_e32 v0, v0, v2
	v_mov_b32_e32 v2, v0
	s_nop 1
	v_permlane32_swap_b32_e32 v0, v2
	v_add_f32_e32 v0, v0, v2
	v_mov_b32_e32 v2, v0
	s_nop 1
	v_permlane16_swap_b32_e32 v0, v2
	s_and_saveexec_b64 s[56:57], vcc
	s_cbranch_execz .LBB0_1911
	v_lshlrev_b64 v[4:5], 6, v[90:91]
	v_lshl_add_u64 v[4:5], s[12:13], 0, v[4:5]
	v_lshl_add_u64 v[4:5], s[54:55], 2, v[4:5]
	s_lshl_b32 s18, s45, 2
	v_lshl_add_u64 v[4:5], v[4:5], 0, s[18:19]
	v_add_f32_e32 v0, v0, v2
	global_store_dword v[4:5], v0, off

; __device__ __forceinline__ u32x4 pack8(f32x4 a, f32x4 b) { u32x4 w; w.x = cvtpk(a[0], a[1]); w.y = cvtpk(a[2], a[3]); w.z = cvtpk(b[0], b[1]); w.w = cvtpk(b[2], b[3]); return w; }
;     __device__ __forceinline__ void operator()(AccRef acc, const Unit& u, int wr, int wc, int fr, int fq) const {
;     ...
;         for (int ai = 0; ai < 2; ++ai) {
;             u32x4 ow[4][2];
; #pragma unroll
;             for (int m = 0; m < 4; ++m)
; #pragma unroll
;                 for (int bj = 0; bj < 2; ++bj)
;                     ow[m][bj] = *(const u32x4*)(hb + (size_t)(u.pm * 256 + ai * 128 + wr * 64 + m * 16 + fr) * D + u.pn * 256 + bj * 128 + wc * 32 + 8 * fq);
;             __builtin_amdgcn_sched_barrier(0);
; #pragma unroll
;             for (int m = 0; m < 4; ++m) {
;                 const int row = u.pm * 256 + ai * 128 + wr * 64 + m * 16 + fr; float part = 0.f;
;                 const float sc = RS ? scale * rst[u.ui * 256 + ai * 128 + wr * 64 + m * 16 + fr] : scale;
; #pragma unroll
;                 for (int bj = 0; bj < 2; ++bj) {
;                     const size_t idx = (size_t)row * D + u.pn * 256 + bj * 128 + wc * 32 + 8 * fq;
;                     const u32x4 o4 = ow[m][bj];
;                     f32x4 v0, v1;
;                     v0[0] = __uint_as_float(o4.x << 16); v0[1] = __uint_as_float(o4.x & 0xffff0000u); v0[2] = __uint_as_float(o4.y << 16); v0[3] = __uint_as_float(o4.y & 0xffff0000u);
;                     v1[0] = __uint_as_float(o4.z << 16); v1[1] = __uint_as_float(o4.z & 0xffff0000u); v1[2] = __uint_as_float(o4.w << 16); v1[3] = __uint_as_float(o4.w & 0xffff0000u);
;                     v0 = v0 + acc[ai][bj][m][0] * sc; v1 = v1 + acc[ai][bj][m][1] * sc;
;                     *(u32x4*)(hb + idx) = pack8(v0, v1);
;                     part += (v0[0] * v0[0] + v0[1] * v0[1]) + (v0[2] * v0[2] + v0[3] * v0[3]) + (v1[0] * v1[0] + v1[1] * v1[1]) + (v1[2] * v1[2] + v1[3] * v1[3]);
;                 }
;                 part = fq_sum(part);
;                 if (fq == 0) ssn[(size_t)row * 16 + u.pn * 4 + wc] = part;
;             }
.LBB0_2093:
	s_or_b64 exec, exec, s[56:57]
	v_add_u32_e32 v102, 0x80, v154
	v_ashrrev_i32_e32 v103, 31, v102
	v_add_u32_e32 v98, 0x90, v154
	v_lshlrev_b64 v[112:113], 11, v[102:103]
	v_ashrrev_i32_e32 v99, 31, v98
	v_add_u32_e32 v94, 0xa0, v154
	v_lshl_add_u64 v[66:67], v[156:157], 0, v[112:113]
	v_lshlrev_b64 v[100:101], 11, v[98:99]
	v_ashrrev_i32_e32 v95, 31, v94
	v_add_u32_e32 v90, 0xb0, v154
	v_lshl_add_u64 v[66:67], v[156:157], 0, v[100:101]
	v_lshlrev_b64 v[96:97], 11, v[94:95]
	v_ashrrev_i32_e32 v91, 31, v90
	v_lshl_add_u64 v[66:67], v[156:157], 0, v[96:97]
	v_lshlrev_b64 v[92:93], 11, v[90:91]
	v_lshl_add_u64 v[66:67], v[156:157], 0, v[92:93]
	s_nop 0
	v_lshl_add_u64 v[112:113], s[10:11], 0, v[112:113]
	v_lshlrev_b32_e32 v114, 16, v186
	v_and_b32_e32 v115, 0xffff0000, v186
	v_lshlrev_b32_e32 v104, 16, v187
	v_and_b32_e32 v105, 0xffff0000, v187
	v_lshlrev_b32_e32 v116, 16, v188
	v_and_b32_e32 v117, 0xffff0000, v188
	v_lshlrev_b32_e32 v106, 16, v189
	v_and_b32_e32 v107, 0xffff0000, v189
	v_lshl_add_u64 v[112:113], s[54:55], 1, v[112:113]
	v_pk_fma_f32 v[64:65], v[64:65], 0.5, v[104:105] op_sel_hi:[1,0,1]
	v_pk_fma_f32 v[62:63], v[62:63], 0.5, v[114:115] op_sel_hi:[1,0,1]
	v_pk_fma_f32 v[104:105], v[60:61], 0.5, v[106:107] op_sel_hi:[1,0,1]
	v_pk_fma_f32 v[106:107], v[58:59], 0.5, v[116:117] op_sel_hi:[1,0,1]
	v_lshl_add_u64 v[112:113], v[112:113], 0, s[18:19]
	v_cvt_pk_bf16_f32 v58, v62, v63
	v_cvt_pk_bf16_f32 v59, v64, v65
	v_cvt_pk_bf16_f32 v60, v106, v107
	v_cvt_pk_bf16_f32 v61, v104, v105
	v_lshl_add_u64 v[112:113], v[112:113], 0, v[0:1]
	global_store_dwordx4 v[112:113], v[58:61], off
	s_nop 1
	v_mul_f32_e32 v58, v63, v63
	v_mul_f32_e32 v59, v65, v65
	v_fmac_f32_e32 v58, v62, v62
	v_fmac_f32_e32 v59, v64, v64
	v_add_f32_e32 v58, v58, v59
	v_mul_f32_e32 v59, v107, v107
	v_fmac_f32_e32 v59, v106, v106
	v_add_f32_e32 v58, v59, v58
	v_mul_f32_e32 v59, v105, v105
	v_fmac_f32_e32 v59, v104, v104
	v_add_f32_e32 v104, v59, v58
	v_lshlrev_b32_e32 v58, 16, v196
	v_and_b32_e32 v59, 0xffff0000, v196
	v_lshlrev_b32_e32 v60, 16, v197
	v_and_b32_e32 v61, 0xffff0000, v197
	v_lshlrev_b32_e32 v62, 16, v198
	v_and_b32_e32 v63, 0xffff0000, v198
	v_lshlrev_b32_e32 v64, 16, v199
	v_and_b32_e32 v65, 0xffff0000, v199
	v_pk_fma_f32 v[56:57], v[56:57], 0.5, v[60:61] op_sel_hi:[1,0,1]
	v_pk_fma_f32 v[54:55], v[54:55], 0.5, v[58:59] op_sel_hi:[1,0,1]
	v_pk_fma_f32 v[58:59], v[52:53], 0.5, v[64:65] op_sel_hi:[1,0,1]
	v_pk_fma_f32 v[60:61], v[50:51], 0.5, v[62:63] op_sel_hi:[1,0,1]
	v_cvt_pk_bf16_f32 v50, v54, v55
	v_cvt_pk_bf16_f32 v51, v56, v57
	v_cvt_pk_bf16_f32 v52, v60, v61
	v_cvt_pk_bf16_f32 v53, v58, v59
	global_store_dwordx4 v[112:113], v[50:53], off offset:256
	s_nop 1
	v_mul_f32_e32 v50, v55, v55
	v_mul_f32_e32 v51, v57, v57
	v_fmac_f32_e32 v50, v54, v54
	v_fmac_f32_e32 v51, v56, v56
	v_add_f32_e32 v50, v50, v51
	v_mul_f32_e32 v51, v61, v61
	v_fmac_f32_e32 v51, v60, v60
	v_add_f32_e32 v50, v51, v50
	v_mul_f32_e32 v51, v59, v59
	v_fmac_f32_e32 v51, v58, v58
	v_add_f32_e32 v50, v51, v50
	v_add_f32_e32 v50, v104, v50
	v_mov_b32_e32 v51, v50
	s_nop 1
	v_permlane32_swap_b32_e32 v50, v51
	v_add_f32_e32 v50, v50, v51
	v_mov_b32_e32 v51, v50
	s_nop 1
	v_permlane16_swap_b32_e32 v50, v51
	s_and_saveexec_b64 s[56:57], vcc
	s_cbranch_execz .LBB0_2095
	v_lshlrev_b64 v[52:53], 6, v[102:103]
	v_lshl_add_u64 v[52:53], s[12:13], 0, v[52:53]
	v_lshl_add_u64 v[52:53], s[52:53], 2, v[52:53]
	s_lshl_b32 s72, s47, 2
	s_mov_b32 s73, s19
	v_lshl_add_u64 v[52:53], v[52:53], 0, s[72:73]
	v_add_f32_e32 v50, v50, v51
	global_store_dword v[52:53], v50, off
.LBB0_2095:
	s_or_b64 exec, exec, s[56:57]
	v_lshlrev_b32_e32 v52, 16, v201
	v_and_b32_e32 v53, 0xffff0000, v201
	v_lshlrev_b32_e32 v54, 16, v202
	v_and_b32_e32 v55, 0xffff0000, v202
	v_pk_fma_f32 v[48:49], v[48:49], 0.5, v[52:53] op_sel_hi:[1,0,1]
	v_pk_fma_f32 v[52:53], v[42:43], 0.5, v[54:55] op_sel_hi:[1,0,1]
	v_lshl_add_u64 v[54:55], s[10:11], 0, v[100:101]
	v_lshlrev_b32_e32 v50, 16, v200
	v_and_b32_e32 v51, 0xffff0000, v200
	v_lshlrev_b32_e32 v56, 16, v203
	v_and_b32_e32 v57, 0xffff0000, v203
	v_lshl_add_u64 v[54:55], s[54:55], 1, v[54:55]
	v_pk_fma_f32 v[46:47], v[46:47], 0.5, v[50:51] op_sel_hi:[1,0,1]
	v_pk_fma_f32 v[50:51], v[44:45], 0.5, v[56:57] op_sel_hi:[1,0,1]
	v_lshl_add_u64 v[54:55], v[54:55], 0, s[18:19]
	v_cvt_pk_bf16_f32 v42, v46, v47
	v_cvt_pk_bf16_f32 v43, v48, v49
	v_cvt_pk_bf16_f32 v44, v52, v53
	v_cvt_pk_bf16_f32 v45, v50, v51
	v_lshl_add_u64 v[54:55], v[54:55], 0, v[0:1]
	global_store_dwordx4 v[54:55], v[42:45], off
	s_nop 1
	v_mul_f32_e32 v42, v47, v47
	v_mul_f32_e32 v43, v49, v49
	v_fmac_f32_e32 v42, v46, v46
	v_fmac_f32_e32 v43, v48, v48
	v_add_f32_e32 v42, v42, v43
	v_mul_f32_e32 v43, v53, v53
	v_fmac_f32_e32 v43, v52, v52
	v_add_f32_e32 v42, v43, v42
	v_mul_f32_e32 v43, v51, v51
	v_fmac_f32_e32 v43, v50, v50
	v_add_f32_e32 v50, v43, v42
	v_lshlrev_b32_e32 v42, 16, v204
	v_and_b32_e32 v43, 0xffff0000, v204
	v_lshlrev_b32_e32 v44, 16, v205
	v_and_b32_e32 v45, 0xffff0000, v205
	v_lshlrev_b32_e32 v46, 16, v206
	v_and_b32_e32 v47, 0xffff0000, v206
	v_lshlrev_b32_e32 v48, 16, v207
	v_and_b32_e32 v49, 0xffff0000, v207
	v_pk_fma_f32 v[40:41], v[40:41], 0.5, v[44:45] op_sel_hi:[1,0,1]
	v_pk_fma_f32 v[38:39], v[38:39], 0.5, v[42:43] op_sel_hi:[1,0,1]
	v_pk_fma_f32 v[42:43], v[36:37], 0.5, v[48:49] op_sel_hi:[1,0,1]
	v_pk_fma_f32 v[44:45], v[34:35], 0.5, v[46:47] op_sel_hi:[1,0,1]
	v_cvt_pk_bf16_f32 v34, v38, v39
	v_cvt_pk_bf16_f32 v35, v40, v41
	v_cvt_pk_bf16_f32 v36, v44, v45
	v_cvt_pk_bf16_f32 v37, v42, v43
	global_store_dwordx4 v[54:55], v[34:37], off offset:256
	s_nop 1
	v_mul_f32_e32 v34, v39, v39
	v_mul_f32_e32 v35, v41, v41
	v_fmac_f32_e32 v34, v38, v38
	v_fmac_f32_e32 v35, v40, v40
	v_add_f32_e32 v34, v34, v35
	v_mul_f32_e32 v35, v45, v45
	v_fmac_f32_e32 v35, v44, v44
	v_add_f32_e32 v34, v35, v34
	v_mul_f32_e32 v35, v43, v43
	v_fmac_f32_e32 v35, v42, v42
	v_add_f32_e32 v34, v35, v34
	v_add_f32_e32 v34, v50, v34
	v_mov_b32_e32 v35, v34
	s_nop 1
	v_permlane32_swap_b32_e32 v34, v35
	v_add_f32_e32 v34, v34, v35
	v_mov_b32_e32 v35, v34
	s_nop 1
	v_permlane16_swap_b32_e32 v34, v35
	s_and_saveexec_b64 s[56:57], vcc
	s_cbranch_execz .LBB0_2097
	v_lshlrev_b64 v[36:37], 6, v[98:99]
	v_lshl_add_u64 v[36:37], s[12:13], 0, v[36:37]
	v_lshl_add_u64 v[36:37], s[52:53], 2, v[36:37]
	s_lshl_b32 s72, s47, 2
	s_mov_b32 s73, s19
	v_lshl_add_u64 v[36:37], v[36:37], 0, s[72:73]
	v_add_f32_e32 v34, v34, v35
	global_store_dword v[36:37], v34, off
; __device__ __forceinline__ u32x4 pack8(f32x4 a, f32x4 b) { u32x4 w; w.x = cvtpk(a[0], a[1]); w.y = cvtpk(a[2], a[3]); w.z = cvtpk(b[0], b[1]); w.w = cvtpk(b[2], b[3]); return w; }
;     __device__ __forceinline__ void operator()(AccRef acc, const Unit& u, int wr, int wc, int fr, int fq) const {
;     ...
;             for (int m = 0; m < 4; ++m) {
;                 const int row = u.pm * 256 + ai * 128 + wr * 64 + m * 16 + fr; float part = 0.f;
;                 const float sc = RS ? scale * rst[u.ui * 256 + ai * 128 + wr * 64 + m * 16 + fr] : scale;
; #pragma unroll
;                 for (int bj = 0; bj < 2; ++bj) {
;                     const size_t idx = (size_t)row * D + u.pn * 256 + bj * 128 + wc * 32 + 8 * fq;
;                     const u32x4 o4 = ow[m][bj];
;                     f32x4 v0, v1;
;                     v0[0] = __uint_as_float(o4.x << 16); v0[1] = __uint_as_float(o4.x & 0xffff0000u); v0[2] = __uint_as_float(o4.y << 16); v0[3] = __uint_as_float(o4.y & 0xffff0000u);
;                     v1[0] = __uint_as_float(o4.z << 16); v1[1] = __uint_as_float(o4.z & 0xffff0000u); v1[2] = __uint_as_float(o4.w << 16); v1[3] = __uint_as_float(o4.w & 0xffff0000u);
;                     v0 = v0 + acc[ai][bj][m][0] * sc; v1 = v1 + acc[ai][bj][m][1] * sc;
;                     *(u32x4*)(hb + idx) = pack8(v0, v1);
;                     part += (v0[0] * v0[0] + v0[1] * v0[1]) + (v0[2] * v0[2] + v0[3] * v0[3]) + (v1[0] * v1[0] + v1[1] * v1[1]) + (v1[2] * v1[2] + v1[3] * v1[3]);
;                 }
;                 part = fq_sum(part);
;                 if (fq == 0) ssn[(size_t)row * 16 + u.pn * 4 + wc] = part;
;             }
.LBB0_2097:
	s_or_b64 exec, exec, s[56:57]
	v_lshlrev_b32_e32 v36, 16, v209
	v_and_b32_e32 v37, 0xffff0000, v209
	v_lshlrev_b32_e32 v38, 16, v210
	v_and_b32_e32 v39, 0xffff0000, v210
	v_pk_fma_f32 v[32:33], v[32:33], 0.5, v[36:37] op_sel_hi:[1,0,1]
	v_pk_fma_f32 v[36:37], v[26:27], 0.5, v[38:39] op_sel_hi:[1,0,1]
	v_lshl_add_u64 v[38:39], s[10:11], 0, v[96:97]
	v_lshlrev_b32_e32 v34, 16, v208
	v_and_b32_e32 v35, 0xffff0000, v208
	v_lshlrev_b32_e32 v40, 16, v211
	v_and_b32_e32 v41, 0xffff0000, v211
	v_lshl_add_u64 v[38:39], s[54:55], 1, v[38:39]
	v_pk_fma_f32 v[30:31], v[30:31], 0.5, v[34:35] op_sel_hi:[1,0,1]
	v_pk_fma_f32 v[34:35], v[28:29], 0.5, v[40:41] op_sel_hi:[1,0,1]
	v_lshl_add_u64 v[38:39], v[38:39], 0, s[18:19]
	v_cvt_pk_bf16_f32 v26, v30, v31
	v_cvt_pk_bf16_f32 v27, v32, v33
	v_cvt_pk_bf16_f32 v28, v36, v37
	v_cvt_pk_bf16_f32 v29, v34, v35
	v_lshl_add_u64 v[38:39], v[38:39], 0, v[0:1]
	global_store_dwordx4 v[38:39], v[26:29], off
	s_nop 1
	v_mul_f32_e32 v26, v31, v31
	v_mul_f32_e32 v27, v33, v33
	v_fmac_f32_e32 v26, v30, v30
	v_fmac_f32_e32 v27, v32, v32
	v_add_f32_e32 v26, v26, v27
	v_mul_f32_e32 v27, v37, v37
	v_fmac_f32_e32 v27, v36, v36
	v_add_f32_e32 v26, v27, v26
	v_mul_f32_e32 v27, v35, v35
	v_fmac_f32_e32 v27, v34, v34
	v_add_f32_e32 v34, v27, v26
	v_lshlrev_b32_e32 v26, 16, v212
	v_and_b32_e32 v27, 0xffff0000, v212
	v_lshlrev_b32_e32 v28, 16, v213
	v_and_b32_e32 v29, 0xffff0000, v213
	v_lshlrev_b32_e32 v30, 16, v214
	v_and_b32_e32 v31, 0xffff0000, v214
	v_lshlrev_b32_e32 v32, 16, v215
	v_and_b32_e32 v33, 0xffff0000, v215
	v_pk_fma_f32 v[24:25], v[24:25], 0.5, v[28:29] op_sel_hi:[1,0,1]
	v_pk_fma_f32 v[22:23], v[22:23], 0.5, v[26:27] op_sel_hi:[1,0,1]
	v_pk_fma_f32 v[26:27], v[20:21], 0.5, v[32:33] op_sel_hi:[1,0,1]
	v_pk_fma_f32 v[28:29], v[18:19], 0.5, v[30:31] op_sel_hi:[1,0,1]
	v_cvt_pk_bf16_f32 v18, v22, v23
	v_cvt_pk_bf16_f32 v19, v24, v25
	v_cvt_pk_bf16_f32 v20, v28, v29
	v_cvt_pk_bf16_f32 v21, v26, v27
	global_store_dwordx4 v[38:39], v[18:21], off offset:256
	s_nop 1
	v_mul_f32_e32 v18, v23, v23
	v_mul_f32_e32 v19, v25, v25
	v_fmac_f32_e32 v18, v22, v22
	v_fmac_f32_e32 v19, v24, v24
	v_add_f32_e32 v18, v18, v19
	v_mul_f32_e32 v19, v29, v29
	v_fmac_f32_e32 v19, v28, v28
	v_add_f32_e32 v18, v19, v18
	v_mul_f32_e32 v19, v27, v27
	v_fmac_f32_e32 v19, v26, v26
	v_add_f32_e32 v18, v19, v18
	v_add_f32_e32 v18, v34, v18
	v_mov_b32_e32 v19, v18
	s_nop 1
	v_permlane32_swap_b32_e32 v18, v19
	v_add_f32_e32 v18, v18, v19
	v_mov_b32_e32 v19, v18
	s_nop 1
	v_permlane16_swap_b32_e32 v18, v19
	s_and_saveexec_b64 s[56:57], vcc
	s_cbranch_execz .LBB0_2099
	v_lshlrev_b64 v[20:21], 6, v[94:95]
	v_lshl_add_u64 v[20:21], s[12:13], 0, v[20:21]
	v_lshl_add_u64 v[20:21], s[52:53], 2, v[20:21]
	s_lshl_b32 s72, s47, 2
	s_mov_b32 s73, s19
	v_lshl_add_u64 v[20:21], v[20:21], 0, s[72:73]
	v_add_f32_e32 v18, v18, v19
	global_store_dword v[20:21], v18, off
.LBB0_2099:
	s_or_b64 exec, exec, s[56:57]
	v_lshlrev_b32_e32 v20, 16, v221
	v_and_b32_e32 v21, 0xffff0000, v221
	v_lshlrev_b32_e32 v22, 16, v222
	v_and_b32_e32 v23, 0xffff0000, v222
	v_pk_fma_f32 v[16:17], v[16:17], 0.5, v[20:21] op_sel_hi:[1,0,1]
	v_pk_fma_f32 v[20:21], v[10:11], 0.5, v[22:23] op_sel_hi:[1,0,1]
	v_lshl_add_u64 v[22:23], s[10:11], 0, v[92:93]
	v_lshlrev_b32_e32 v18, 16, v220
	v_and_b32_e32 v19, 0xffff0000, v220
	v_lshlrev_b32_e32 v24, 16, v223
	v_and_b32_e32 v25, 0xffff0000, v223
	v_lshl_add_u64 v[22:23], s[54:55], 1, v[22:23]
	v_pk_fma_f32 v[14:15], v[14:15], 0.5, v[18:19] op_sel_hi:[1,0,1]
	v_pk_fma_f32 v[18:19], v[12:13], 0.5, v[24:25] op_sel_hi:[1,0,1]
	v_lshl_add_u64 v[22:23], v[22:23], 0, s[18:19]
	v_cvt_pk_bf16_f32 v10, v14, v15
	v_cvt_pk_bf16_f32 v11, v16, v17
	v_cvt_pk_bf16_f32 v12, v20, v21
	v_cvt_pk_bf16_f32 v13, v18, v19
	v_lshl_add_u64 v[22:23], v[22:23], 0, v[0:1]
	global_store_dwordx4 v[22:23], v[10:13], off
	v_mul_f32_e32 v0, v15, v15
	v_fmac_f32_e32 v0, v14, v14
	v_mul_f32_e32 v10, v17, v17
	v_fmac_f32_e32 v10, v16, v16
	v_add_f32_e32 v0, v0, v10
	v_mul_f32_e32 v10, v21, v21
	v_fmac_f32_e32 v10, v20, v20
	v_add_f32_e32 v0, v10, v0
	v_mul_f32_e32 v10, v19, v19
	v_fmac_f32_e32 v10, v18, v18
	v_add_f32_e32 v0, v10, v0
	v_lshlrev_b32_e32 v10, 16, v238
	v_and_b32_e32 v11, 0xffff0000, v238
	v_lshlrev_b32_e32 v12, 16, v239
	v_and_b32_e32 v13, 0xffff0000, v239
	v_lshlrev_b32_e32 v14, 16, v240
	v_and_b32_e32 v15, 0xffff0000, v240
	v_lshlrev_b32_e32 v16, 16, v241
	v_and_b32_e32 v17, 0xffff0000, v241
	v_pk_fma_f32 v[8:9], v[8:9], 0.5, v[12:13] op_sel_hi:[1,0,1]
	v_pk_fma_f32 v[6:7], v[6:7], 0.5, v[10:11] op_sel_hi:[1,0,1]
	v_pk_fma_f32 v[10:11], v[4:5], 0.5, v[16:17] op_sel_hi:[1,0,1]
	v_pk_fma_f32 v[12:13], v[2:3], 0.5, v[14:15] op_sel_hi:[1,0,1]
	v_cvt_pk_bf16_f32 v2, v6, v7
	v_cvt_pk_bf16_f32 v3, v8, v9
	v_cvt_pk_bf16_f32 v4, v12, v13
	v_cvt_pk_bf16_f32 v5, v10, v11
	global_store_dwordx4 v[22:23], v[2:5], off offset:256
	s_nop 1
	v_mul_f32_e32 v2, v7, v7
	v_mul_f32_e32 v3, v9, v9
	v_fmac_f32_e32 v2, v6, v6
	v_fmac_f32_e32 v3, v8, v8
	v_add_f32_e32 v2, v2, v3
	v_mul_f32_e32 v3, v13, v13
	v_fmac_f32_e32 v3, v12, v12
	v_add_f32_e32 v2, v3, v2
	v_mul_f32_e32 v3, v11, v11
	v_fmac_f32_e32 v3, v10, v10
	v_add_f32_e32 v2, v3, v2
	v_add_f32_e32 v0, v0, v2
	v_mov_b32_e32 v2, v0
	s_nop 1
	v_permlane32_swap_b32_e32 v0, v2
	v_add_f32_e32 v0, v0, v2
	v_mov_b32_e32 v2, v0
	s_nop 1
	v_permlane16_swap_b32_e32 v0, v2
	s_and_saveexec_b64 s[54:55], vcc
	s_cbranch_execz .LBB0_2101
	v_lshlrev_b64 v[4:5], 6, v[90:91]
	v_lshl_add_u64 v[4:5], s[12:13], 0, v[4:5]
	v_lshl_add_u64 v[4:5], s[52:53], 2, v[4:5]
	s_lshl_b32 s18, s47, 2
	v_lshl_add_u64 v[4:5], v[4:5], 0, s[18:19]
	v_add_f32_e32 v0, v0, v2
	global_store_dword v[4:5], v0, off
